# k8 stack + chalf skip branches moved before their barriers in proj/gate_up K-loops (out-of-line barrier stubs for half units), so no branch sits between barrier release and the first MFMA
# speedup vs baseline: 1.0053x; 1.0053x over previous
.LBB0_167:
	s_add_u32 s26, s6, s0
	s_addc_u32 s27, s7, s1
	s_add_u32 s66, s26, 0x100
	s_addc_u32 s67, s27, 0
	s_add_u32 vcc_lo, s69, s0
	s_addc_u32 vcc_hi, s70, s1
	s_cmpk_eq_i32 s0, 0xf00
	s_cselect_b64 s[26:27], -1, 0
	s_and_b64 s[48:49], s[26:27], exec
	s_cselect_b32 s49, s29, vcc_hi
	s_cselect_b32 s48, s68, vcc_lo
	s_mov_b32 m0, s80
	s_cselect_b32 s67, s5, s67
	s_cselect_b32 s66, s47, s66
	v_lshl_add_u64 v[2:3], s[48:49], 0, v[210:211]
	s_add_u32 vcc_lo, s48, 0x80000
	global_load_lds_dwordx4 v[2:3], off
	v_lshl_add_u64 v[226:227], s[48:49], 0, v[214:215]
	s_mov_b32 m0, s81
	s_addc_u32 vcc_hi, s49, 0
	global_load_lds_dwordx4 v[226:227], off
	v_lshl_add_u64 v[196:197], vcc, 0, v[210:211]
	s_mov_b32 m0, s82
	v_lshl_add_u64 v[228:229], s[66:67], 0, v[208:209]
	global_load_lds_dwordx4 v[196:197], off
	v_lshl_add_u64 v[196:197], vcc, 0, v[214:215]
	s_mov_b32 m0, s83
	v_lshl_add_u64 v[230:231], s[66:67], 0, v[212:213]
	global_load_lds_dwordx4 v[196:197], off
	s_mov_b32 m0, s77
	s_and_b64 vcc, exec, s[44:45]
	global_load_lds_dwordx4 v[228:229], off
	s_mov_b32 m0, s84
	s_nop 0
	global_load_lds_dwordx4 v[230:231], off
	s_waitcnt vmcnt(8)
	s_waitcnt lgkmcnt(0)
	s_cbranch_vccnz .Lskp_p1
	s_barrier
	s_setprio 1
	s_waitcnt lgkmcnt(0)
	v_mfma_f32_16x16x32_bf16 v[64:67], v[148:151], v[176:179], v[64:67]
	v_mfma_f32_16x16x32_bf16 v[60:63], v[156:159], v[176:179], v[60:63]
	v_mfma_f32_16x16x32_bf16 v[48:51], v[148:151], v[172:175], v[48:51]
	v_mfma_f32_16x16x32_bf16 v[44:47], v[156:159], v[172:175], v[44:47]
	v_mfma_f32_16x16x32_bf16 v[32:35], v[148:151], v[168:171], v[32:35]
	v_mfma_f32_16x16x32_bf16 v[28:31], v[156:159], v[168:171], v[28:31]
	v_mfma_f32_16x16x32_bf16 v[16:19], v[148:151], v[164:167], v[16:19]
	v_mfma_f32_16x16x32_bf16 v[12:15], v[156:159], v[164:167], v[12:15]
	v_mfma_f32_16x16x32_bf16 v[64:67], v[152:155], v[192:195], v[64:67]
	v_mfma_f32_16x16x32_bf16 v[60:63], v[160:163], v[192:195], v[60:63]
	v_mfma_f32_16x16x32_bf16 v[48:51], v[152:155], v[188:191], v[48:51]
	v_mfma_f32_16x16x32_bf16 v[44:47], v[160:163], v[188:191], v[44:47]
	v_mfma_f32_16x16x32_bf16 v[32:35], v[152:155], v[184:187], v[32:35]
	v_mfma_f32_16x16x32_bf16 v[28:31], v[160:163], v[184:187], v[28:31]
	v_mfma_f32_16x16x32_bf16 v[16:19], v[152:155], v[180:183], v[16:19]
	v_mfma_f32_16x16x32_bf16 v[12:15], v[160:163], v[180:183], v[12:15]
	s_setprio 0
	s_setprio 1
	v_mfma_f32_16x16x32_bf16 v[56:59], v[132:135], v[176:179], v[56:59]
	v_mfma_f32_16x16x32_bf16 v[52:55], v[140:143], v[176:179], v[52:55]
	v_mfma_f32_16x16x32_bf16 v[40:43], v[132:135], v[172:175], v[40:43]
	v_mfma_f32_16x16x32_bf16 v[36:39], v[140:143], v[172:175], v[36:39]
	v_mfma_f32_16x16x32_bf16 v[24:27], v[132:135], v[168:171], v[24:27]
	v_mfma_f32_16x16x32_bf16 v[20:23], v[140:143], v[168:171], v[20:23]
	v_mfma_f32_16x16x32_bf16 v[8:11], v[132:135], v[164:167], v[8:11]
	v_mfma_f32_16x16x32_bf16 v[4:7], v[140:143], v[164:167], v[4:7]
	v_mfma_f32_16x16x32_bf16 v[56:59], v[136:139], v[192:195], v[56:59]
	v_mfma_f32_16x16x32_bf16 v[52:55], v[144:147], v[192:195], v[52:55]
	v_mfma_f32_16x16x32_bf16 v[40:43], v[136:139], v[188:191], v[40:43]
	v_mfma_f32_16x16x32_bf16 v[36:39], v[144:147], v[188:191], v[36:39]
	v_mfma_f32_16x16x32_bf16 v[24:27], v[136:139], v[184:187], v[24:27]
	v_mfma_f32_16x16x32_bf16 v[20:23], v[144:147], v[184:187], v[20:23]
	v_mfma_f32_16x16x32_bf16 v[8:11], v[136:139], v[180:183], v[8:11]
	v_mfma_f32_16x16x32_bf16 v[4:7], v[144:147], v[180:183], v[4:7]
	s_setprio 0

.LBB0_171:
	s_mov_b32 m0, s58
	v_lshl_add_u64 v[2:3], v[2:3], 0, s[72:73]
	s_add_u32 s26, s48, 0x80080
	global_load_lds_dwordx4 v[2:3], off
	v_lshl_add_u64 v[2:3], v[226:227], 0, s[72:73]
	s_mov_b32 m0, s59
	s_addc_u32 s27, s49, 0
	global_load_lds_dwordx4 v[2:3], off
	v_lshl_add_u64 v[2:3], s[26:27], 0, v[210:211]
	s_mov_b32 m0, s62
	s_and_b64 vcc, exec, s[44:45]
	global_load_lds_dwordx4 v[2:3], off
	v_lshl_add_u64 v[2:3], s[26:27], 0, v[214:215]
	s_mov_b32 m0, s63
	s_nop 0
	global_load_lds_dwordx4 v[2:3], off
	v_lshl_add_u64 v[2:3], v[228:229], 0, s[72:73]
	s_mov_b32 m0, s60
	s_nop 0
	global_load_lds_dwordx4 v[2:3], off
	v_lshl_add_u64 v[2:3], v[230:231], 0, s[72:73]
	s_mov_b32 m0, s61
	s_nop 0
	global_load_lds_dwordx4 v[2:3], off
	s_waitcnt vmcnt(8)
	s_waitcnt lgkmcnt(0)
	s_cbranch_vccnz .Lskp_p2
	s_barrier
	s_setprio 1
	s_waitcnt lgkmcnt(0)
	v_mfma_f32_16x16x32_bf16 v[64:67], v[148:151], v[176:179], v[64:67]
	v_mfma_f32_16x16x32_bf16 v[60:63], v[156:159], v[176:179], v[60:63]
	v_mfma_f32_16x16x32_bf16 v[48:51], v[148:151], v[172:175], v[48:51]
	v_mfma_f32_16x16x32_bf16 v[44:47], v[156:159], v[172:175], v[44:47]
	v_mfma_f32_16x16x32_bf16 v[32:35], v[148:151], v[168:171], v[32:35]
	v_mfma_f32_16x16x32_bf16 v[28:31], v[156:159], v[168:171], v[28:31]
	v_mfma_f32_16x16x32_bf16 v[16:19], v[148:151], v[164:167], v[16:19]
	v_mfma_f32_16x16x32_bf16 v[12:15], v[156:159], v[164:167], v[12:15]
	v_mfma_f32_16x16x32_bf16 v[64:67], v[152:155], v[192:195], v[64:67]
	v_mfma_f32_16x16x32_bf16 v[60:63], v[160:163], v[192:195], v[60:63]
	v_mfma_f32_16x16x32_bf16 v[48:51], v[152:155], v[188:191], v[48:51]
	v_mfma_f32_16x16x32_bf16 v[44:47], v[160:163], v[188:191], v[44:47]
	v_mfma_f32_16x16x32_bf16 v[32:35], v[152:155], v[184:187], v[32:35]
	v_mfma_f32_16x16x32_bf16 v[28:31], v[160:163], v[184:187], v[28:31]
	v_mfma_f32_16x16x32_bf16 v[16:19], v[152:155], v[180:183], v[16:19]
	v_mfma_f32_16x16x32_bf16 v[12:15], v[160:163], v[180:183], v[12:15]
	s_setprio 0
	s_setprio 1
	v_mfma_f32_16x16x32_bf16 v[56:59], v[132:135], v[176:179], v[56:59]
	v_mfma_f32_16x16x32_bf16 v[52:55], v[140:143], v[176:179], v[52:55]
	v_mfma_f32_16x16x32_bf16 v[40:43], v[132:135], v[172:175], v[40:43]
	v_mfma_f32_16x16x32_bf16 v[36:39], v[140:143], v[172:175], v[36:39]
	v_mfma_f32_16x16x32_bf16 v[24:27], v[132:135], v[168:171], v[24:27]
	v_mfma_f32_16x16x32_bf16 v[20:23], v[140:143], v[168:171], v[20:23]
	v_mfma_f32_16x16x32_bf16 v[8:11], v[132:135], v[164:167], v[8:11]
	v_mfma_f32_16x16x32_bf16 v[2:5], v[140:143], v[164:167], v[4:7]
	v_mfma_f32_16x16x32_bf16 v[56:59], v[136:139], v[192:195], v[56:59]
	v_mfma_f32_16x16x32_bf16 v[52:55], v[144:147], v[192:195], v[52:55]
	v_mfma_f32_16x16x32_bf16 v[40:43], v[136:139], v[188:191], v[40:43]
	v_mfma_f32_16x16x32_bf16 v[36:39], v[144:147], v[188:191], v[36:39]
	v_mfma_f32_16x16x32_bf16 v[24:27], v[136:139], v[184:187], v[24:27]
	v_mfma_f32_16x16x32_bf16 v[20:23], v[144:147], v[184:187], v[20:23]
	v_mfma_f32_16x16x32_bf16 v[8:11], v[136:139], v[180:183], v[8:11]
	v_mfma_f32_16x16x32_bf16 v[4:7], v[144:147], v[180:183], v[2:5]
	s_setprio 0
.LBB0_164:
	s_barrier
	s_add_i32 s19, s19, 2
	s_add_u32 s0, s0, 0x100
	s_addc_u32 s1, s1, 0
	s_cmp_gt_u32 s19, 29
	s_cbranch_scc0 .LBB0_165
	s_branch .LBB0_173
.Lskp_p1:
	s_barrier
	s_branch .LBB0_169
.Lskp_p2:
	s_barrier
	s_branch .LBB0_164
	s_nop 0
	s_nop 0
	s_nop 0

.LBB0_683:
	s_add_u32 s16, s10, s0
	s_addc_u32 s17, s11, s1
	s_add_u32 s20, s16, 0x100
	s_addc_u32 s21, s17, 0
	s_add_u32 s70, s55, s0
	s_addc_u32 s71, s68, s1
	s_cmpk_eq_i32 s0, 0xf00
	s_cselect_b64 s[26:27], -1, 0
	s_and_b64 s[16:17], s[26:27], exec
	s_cselect_b32 s17, s35, s71
	s_cselect_b32 s16, s47, s70
	s_mov_b32 m0, s36
	s_cselect_b32 s21, s33, s21
	s_cselect_b32 s20, s34, s20
	v_lshl_add_u64 v[2:3], s[16:17], 0, v[212:213]
	s_add_u32 s70, s16, 0x80000
	global_load_lds_dwordx4 v[2:3], off
	v_lshl_add_u64 v[224:225], s[16:17], 0, v[208:209]
	s_mov_b32 m0, s37
	s_addc_u32 s71, s17, 0
	global_load_lds_dwordx4 v[224:225], off
	v_lshl_add_u64 v[196:197], s[70:71], 0, v[212:213]
	s_mov_b32 m0, s48
	v_lshl_add_u64 v[226:227], s[20:21], 0, v[214:215]
	global_load_lds_dwordx4 v[196:197], off
	v_lshl_add_u64 v[196:197], s[70:71], 0, v[208:209]
	s_mov_b32 m0, s49
	v_lshl_add_u64 v[228:229], s[20:21], 0, v[210:211]
	global_load_lds_dwordx4 v[196:197], off
	s_mov_b32 m0, s31
	s_and_b64 vcc, exec, s[40:41]
	global_load_lds_dwordx4 v[226:227], off
	s_mov_b32 m0, s50
	s_nop 0
	global_load_lds_dwordx4 v[228:229], off
	s_waitcnt vmcnt(8)
	s_waitcnt lgkmcnt(0)
	s_cbranch_vccnz .Lskp_g1
	s_barrier
	s_setprio 1
	s_waitcnt lgkmcnt(0)
	v_mfma_f32_16x16x32_bf16 v[64:67], v[148:151], v[176:179], v[64:67]
	v_mfma_f32_16x16x32_bf16 v[60:63], v[156:159], v[176:179], v[60:63]
	v_mfma_f32_16x16x32_bf16 v[48:51], v[148:151], v[172:175], v[48:51]
	v_mfma_f32_16x16x32_bf16 v[44:47], v[156:159], v[172:175], v[44:47]
	v_mfma_f32_16x16x32_bf16 v[32:35], v[148:151], v[168:171], v[32:35]
	v_mfma_f32_16x16x32_bf16 v[28:31], v[156:159], v[168:171], v[28:31]
	v_mfma_f32_16x16x32_bf16 v[16:19], v[148:151], v[164:167], v[16:19]
	v_mfma_f32_16x16x32_bf16 v[12:15], v[156:159], v[164:167], v[12:15]
	v_mfma_f32_16x16x32_bf16 v[64:67], v[152:155], v[192:195], v[64:67]
	v_mfma_f32_16x16x32_bf16 v[60:63], v[160:163], v[192:195], v[60:63]
	v_mfma_f32_16x16x32_bf16 v[48:51], v[152:155], v[188:191], v[48:51]
	v_mfma_f32_16x16x32_bf16 v[44:47], v[160:163], v[188:191], v[44:47]
	v_mfma_f32_16x16x32_bf16 v[32:35], v[152:155], v[184:187], v[32:35]
	v_mfma_f32_16x16x32_bf16 v[28:31], v[160:163], v[184:187], v[28:31]
	v_mfma_f32_16x16x32_bf16 v[16:19], v[152:155], v[180:183], v[16:19]
	v_mfma_f32_16x16x32_bf16 v[12:15], v[160:163], v[180:183], v[12:15]
	s_setprio 0
	s_setprio 1
	v_mfma_f32_16x16x32_bf16 v[56:59], v[132:135], v[176:179], v[56:59]
	v_mfma_f32_16x16x32_bf16 v[52:55], v[140:143], v[176:179], v[52:55]
	v_mfma_f32_16x16x32_bf16 v[40:43], v[132:135], v[172:175], v[40:43]
	v_mfma_f32_16x16x32_bf16 v[36:39], v[140:143], v[172:175], v[36:39]
	v_mfma_f32_16x16x32_bf16 v[24:27], v[132:135], v[168:171], v[24:27]
	v_mfma_f32_16x16x32_bf16 v[20:23], v[140:143], v[168:171], v[20:23]
	v_mfma_f32_16x16x32_bf16 v[8:11], v[132:135], v[164:167], v[8:11]
	v_mfma_f32_16x16x32_bf16 v[4:7], v[140:143], v[164:167], v[4:7]
	v_mfma_f32_16x16x32_bf16 v[56:59], v[136:139], v[192:195], v[56:59]
	v_mfma_f32_16x16x32_bf16 v[52:55], v[144:147], v[192:195], v[52:55]
	v_mfma_f32_16x16x32_bf16 v[40:43], v[136:139], v[188:191], v[40:43]
	v_mfma_f32_16x16x32_bf16 v[36:39], v[144:147], v[188:191], v[36:39]
	v_mfma_f32_16x16x32_bf16 v[24:27], v[136:139], v[184:187], v[24:27]
	v_mfma_f32_16x16x32_bf16 v[20:23], v[144:147], v[184:187], v[20:23]
	v_mfma_f32_16x16x32_bf16 v[8:11], v[136:139], v[180:183], v[8:11]
	v_mfma_f32_16x16x32_bf16 v[4:7], v[144:147], v[180:183], v[4:7]
	s_setprio 0

.LBB0_687:
	s_mov_b32 m0, s61
	v_lshl_add_u64 v[2:3], v[2:3], 0, s[72:73]
	s_add_u32 s16, s16, 0x80080
	global_load_lds_dwordx4 v[2:3], off
	v_lshl_add_u64 v[2:3], v[224:225], 0, s[72:73]
	s_mov_b32 m0, s62
	s_addc_u32 s17, s17, 0
	global_load_lds_dwordx4 v[2:3], off
	v_lshl_add_u64 v[2:3], s[16:17], 0, v[212:213]
	s_mov_b32 m0, s65
	s_and_b64 vcc, exec, s[40:41]
	global_load_lds_dwordx4 v[2:3], off
	v_lshl_add_u64 v[2:3], s[16:17], 0, v[208:209]
	s_mov_b32 m0, s66
	s_nop 0
	global_load_lds_dwordx4 v[2:3], off
	v_lshl_add_u64 v[2:3], v[226:227], 0, s[72:73]
	s_mov_b32 m0, s63
	s_nop 0
	global_load_lds_dwordx4 v[2:3], off
	v_lshl_add_u64 v[2:3], v[228:229], 0, s[72:73]
	s_mov_b32 m0, s64
	s_nop 0
	global_load_lds_dwordx4 v[2:3], off
	s_waitcnt vmcnt(8)
	s_waitcnt lgkmcnt(0)
	s_cbranch_vccnz .Lskp_g2
	s_barrier
	s_setprio 1
	s_waitcnt lgkmcnt(0)
	v_mfma_f32_16x16x32_bf16 v[64:67], v[148:151], v[176:179], v[64:67]
	v_mfma_f32_16x16x32_bf16 v[60:63], v[156:159], v[176:179], v[60:63]
	v_mfma_f32_16x16x32_bf16 v[48:51], v[148:151], v[172:175], v[48:51]
	v_mfma_f32_16x16x32_bf16 v[44:47], v[156:159], v[172:175], v[44:47]
	v_mfma_f32_16x16x32_bf16 v[32:35], v[148:151], v[168:171], v[32:35]
	v_mfma_f32_16x16x32_bf16 v[28:31], v[156:159], v[168:171], v[28:31]
	v_mfma_f32_16x16x32_bf16 v[16:19], v[148:151], v[164:167], v[16:19]
	v_mfma_f32_16x16x32_bf16 v[12:15], v[156:159], v[164:167], v[12:15]
	v_mfma_f32_16x16x32_bf16 v[64:67], v[152:155], v[192:195], v[64:67]
	v_mfma_f32_16x16x32_bf16 v[60:63], v[160:163], v[192:195], v[60:63]
	v_mfma_f32_16x16x32_bf16 v[48:51], v[152:155], v[188:191], v[48:51]
	v_mfma_f32_16x16x32_bf16 v[44:47], v[160:163], v[188:191], v[44:47]
	v_mfma_f32_16x16x32_bf16 v[32:35], v[152:155], v[184:187], v[32:35]
	v_mfma_f32_16x16x32_bf16 v[28:31], v[160:163], v[184:187], v[28:31]
	v_mfma_f32_16x16x32_bf16 v[16:19], v[152:155], v[180:183], v[16:19]
	v_mfma_f32_16x16x32_bf16 v[12:15], v[160:163], v[180:183], v[12:15]
	s_setprio 0
	s_setprio 1
	v_mfma_f32_16x16x32_bf16 v[56:59], v[132:135], v[176:179], v[56:59]
	v_mfma_f32_16x16x32_bf16 v[52:55], v[140:143], v[176:179], v[52:55]
	v_mfma_f32_16x16x32_bf16 v[40:43], v[132:135], v[172:175], v[40:43]
	v_mfma_f32_16x16x32_bf16 v[36:39], v[140:143], v[172:175], v[36:39]
	v_mfma_f32_16x16x32_bf16 v[24:27], v[132:135], v[168:171], v[24:27]
	v_mfma_f32_16x16x32_bf16 v[20:23], v[140:143], v[168:171], v[20:23]
	v_mfma_f32_16x16x32_bf16 v[8:11], v[132:135], v[164:167], v[8:11]
	v_mfma_f32_16x16x32_bf16 v[2:5], v[140:143], v[164:167], v[4:7]
	v_mfma_f32_16x16x32_bf16 v[56:59], v[136:139], v[192:195], v[56:59]
	v_mfma_f32_16x16x32_bf16 v[52:55], v[144:147], v[192:195], v[52:55]
	v_mfma_f32_16x16x32_bf16 v[40:43], v[136:139], v[188:191], v[40:43]
	v_mfma_f32_16x16x32_bf16 v[36:39], v[144:147], v[188:191], v[36:39]
	v_mfma_f32_16x16x32_bf16 v[24:27], v[136:139], v[184:187], v[24:27]
	v_mfma_f32_16x16x32_bf16 v[20:23], v[144:147], v[184:187], v[20:23]
	v_mfma_f32_16x16x32_bf16 v[8:11], v[136:139], v[180:183], v[8:11]
	v_mfma_f32_16x16x32_bf16 v[4:7], v[144:147], v[180:183], v[2:5]
	s_setprio 0
.LBB0_680:
	s_barrier
	s_add_i32 s69, s69, 2
	s_add_u32 s0, s0, 0x100
	s_addc_u32 s1, s1, 0
	s_cmp_gt_u32 s69, 29
	s_cbranch_scc0 .LBB0_681
	s_branch .LBB0_689
